# P4 row loop: both rows' residual/mix/mix2 pieces of a 16-row chunk loaded up front, one wait per chunk (on top of prologue hoist)
# baseline (speedup 1.0000x reference)
.LBB0_613:
	s_add_i32 s36, s23, s9
	s_mov_b32 s98, s36
	s_mov_b32 s99, 0
	s_lshl_b64 s[98:99], s[98:99], 12
	s_and_b64 vcc, exec, s[0:1]
	s_cbranch_vccz .Lpf4_a
	v_lshl_add_u64 v[196:197], v[40:41], 0, s[98:99]
	global_load_dwordx4 v[100:103], v[196:197], off
	global_load_dwordx4 v[104:107], v[196:197], off offset:1024
	global_load_dwordx4 v[108:111], v[196:197], off offset:2048
	global_load_dwordx4 v[112:115], v[196:197], off offset:3072
	s_add_u32 s98, s98, 0x1000
	s_addc_u32 s99, s99, 0
	v_lshl_add_u64 v[198:199], v[40:41], 0, s[98:99]
	global_load_dwordx4 v[116:119], v[198:199], off
	global_load_dwordx4 v[120:123], v[198:199], off offset:1024
	global_load_dwordx4 v[124:127], v[198:199], off offset:2048
	global_load_dwordx4 v[128:131], v[198:199], off offset:3072
	s_sub_u32 s98, s98, 0x1000
	s_subb_u32 s99, s99, 0
.Lpf4_a:
	v_lshl_add_u64 v[196:197], v[38:39], 0, s[98:99]
	global_load_dwordx4 v[132:135], v[196:197], off
	global_load_dwordx4 v[136:139], v[196:197], off offset:1024
	global_load_dwordx4 v[140:143], v[196:197], off offset:2048
	global_load_dwordx4 v[144:147], v[196:197], off offset:3072
	s_add_u32 s98, s98, 0x1000
	s_addc_u32 s99, s99, 0
	v_lshl_add_u64 v[198:199], v[38:39], 0, s[98:99]
	global_load_dwordx4 v[148:151], v[198:199], off
	global_load_dwordx4 v[152:155], v[198:199], off offset:1024
	global_load_dwordx4 v[156:159], v[198:199], off offset:2048
	global_load_dwordx4 v[160:163], v[198:199], off offset:3072
	s_cmpk_lt_i32 s36, 0x2000
	s_cbranch_scc1 .Lpf4_b
	s_add_i32 s98, s36, 0xffffe000
	s_mov_b32 s99, 0
	s_lshl_b64 s[98:99], s[98:99], 12
	v_lshl_add_u64 v[196:197], v[42:43], 0, s[98:99]
	global_load_dwordx4 v[164:167], v[196:197], off
	global_load_dwordx4 v[168:171], v[196:197], off offset:1024
	global_load_dwordx4 v[172:175], v[196:197], off offset:2048
	global_load_dwordx4 v[176:179], v[196:197], off offset:3072
	s_add_u32 s98, s98, 0x1000
	s_addc_u32 s99, s99, 0
	v_lshl_add_u64 v[198:199], v[42:43], 0, s[98:99]
	global_load_dwordx4 v[180:183], v[198:199], off
	global_load_dwordx4 v[184:187], v[198:199], off offset:1024
	global_load_dwordx4 v[188:191], v[198:199], off offset:2048
	global_load_dwordx4 v[192:195], v[198:199], off offset:3072
.Lpf4_b:
	s_waitcnt vmcnt(0)
	s_cmpk_lt_i32 s36, 0x2000
	s_cselect_b64 s[68:69], -1, 0
	s_cmpk_gt_i32 s36, 0x1fff
	s_cselect_b64 s[72:73], -1, 0
	s_and_b64 vcc, exec, s[0:1]
	s_cbranch_vccz .LBB0_615
	s_ashr_i32 s37, s36, 31
	s_lshl_b64 s[12:13], s[36:37], 12
	v_lshl_add_u64 v[16:17], v[40:41], 0, s[12:13]
	v_mov_b64_e32 v[4:5], v[100:101]
	v_mov_b64_e32 v[6:7], v[102:103]
	v_mov_b64_e32 v[8:9], v[104:105]
	v_mov_b64_e32 v[10:11], v[106:107]
	v_mov_b64_e32 v[12:13], v[108:109]
	v_mov_b64_e32 v[14:15], v[110:111]
	v_mov_b64_e32 v[46:47], v[112:113]
	v_mov_b64_e32 v[48:49], v[114:115]
	v_lshlrev_b32_e32 v32, 16, v4
	v_and_b32_e32 v33, 0xffff0000, v4
	v_lshlrev_b32_e32 v34, 16, v5
	v_and_b32_e32 v35, 0xffff0000, v5
	v_lshlrev_b32_e32 v28, 16, v6
	v_and_b32_e32 v29, 0xffff0000, v6
	v_lshlrev_b32_e32 v30, 16, v7
	v_and_b32_e32 v31, 0xffff0000, v7
	v_lshlrev_b32_e32 v24, 16, v8
	v_and_b32_e32 v25, 0xffff0000, v8
	v_lshlrev_b32_e32 v26, 16, v9
	v_and_b32_e32 v27, 0xffff0000, v9
	v_lshlrev_b32_e32 v20, 16, v10
	v_and_b32_e32 v21, 0xffff0000, v10
	v_lshlrev_b32_e32 v22, 16, v11
	v_and_b32_e32 v23, 0xffff0000, v11
	v_lshlrev_b32_e32 v16, 16, v12
	v_and_b32_e32 v17, 0xffff0000, v12
	v_lshlrev_b32_e32 v18, 16, v13
	v_and_b32_e32 v19, 0xffff0000, v13
	v_lshlrev_b32_e32 v12, 16, v14
	v_and_b32_e32 v13, 0xffff0000, v14
	v_lshlrev_b32_e32 v14, 16, v15
	v_and_b32_e32 v15, 0xffff0000, v15
	v_lshlrev_b32_e32 v8, 16, v46
	v_and_b32_e32 v9, 0xffff0000, v46
	v_lshlrev_b32_e32 v10, 16, v47
	v_and_b32_e32 v11, 0xffff0000, v47
	v_lshlrev_b32_e32 v4, 16, v48
	v_and_b32_e32 v5, 0xffff0000, v48
	v_lshlrev_b32_e32 v6, 16, v49
	v_and_b32_e32 v7, 0xffff0000, v49
	s_cbranch_execz .LBB0_616
	s_branch .LBB0_621

.LBB0_621:
	s_lshl_b64 s[12:13], s[36:37], 12
	v_lshl_add_u64 v[58:59], v[38:39], 0, s[12:13]
	v_mov_b64_e32 v[46:47], v[132:133]
	v_mov_b64_e32 v[48:49], v[134:135]
	v_mov_b64_e32 v[50:51], v[136:137]
	v_mov_b64_e32 v[52:53], v[138:139]
	v_mov_b64_e32 v[54:55], v[140:141]
	v_mov_b64_e32 v[56:57], v[142:143]
	v_mov_b64_e32 v[78:79], v[144:145]
	v_mov_b64_e32 v[80:81], v[146:147]
	s_cmpk_lt_i32 s36, 0x2000
	s_waitcnt vmcnt(0)
	v_lshlrev_b32_e32 v74, 16, v46
	v_and_b32_e32 v75, 0xffff0000, v46
	v_lshlrev_b32_e32 v76, 16, v47
	v_and_b32_e32 v77, 0xffff0000, v47
	v_lshlrev_b32_e32 v70, 16, v48
	v_and_b32_e32 v71, 0xffff0000, v48
	v_lshlrev_b32_e32 v72, 16, v49
	v_and_b32_e32 v73, 0xffff0000, v49
	v_lshlrev_b32_e32 v66, 16, v50
	v_and_b32_e32 v67, 0xffff0000, v50
	v_lshlrev_b32_e32 v68, 16, v51
	v_and_b32_e32 v69, 0xffff0000, v51
	v_lshlrev_b32_e32 v62, 16, v52
	v_and_b32_e32 v63, 0xffff0000, v52
	v_lshlrev_b32_e32 v64, 16, v53
	v_and_b32_e32 v65, 0xffff0000, v53
	v_lshlrev_b32_e32 v60, 16, v54
	v_and_b32_e32 v61, 0xffff0000, v54
	v_lshlrev_b32_e32 v58, 16, v55
	v_and_b32_e32 v59, 0xffff0000, v55
	v_lshlrev_b32_e32 v54, 16, v56
	v_and_b32_e32 v55, 0xffff0000, v56
	v_lshlrev_b32_e32 v56, 16, v57
	v_and_b32_e32 v57, 0xffff0000, v57
	v_lshlrev_b32_e32 v50, 16, v78
	v_and_b32_e32 v51, 0xffff0000, v78
	v_lshlrev_b32_e32 v52, 16, v79
	v_and_b32_e32 v53, 0xffff0000, v79
	v_lshlrev_b32_e32 v48, 16, v80
	v_and_b32_e32 v49, 0xffff0000, v80
	v_lshlrev_b32_e32 v46, 16, v81
	v_and_b32_e32 v47, 0xffff0000, v81
	s_cbranch_scc1 .LBB0_623
	s_add_i32 s64, s36, 0xffffe000
	s_lshl_b64 s[12:13], s[64:65], 12
	v_lshl_add_u64 v[82:83], v[42:43], 0, s[12:13]
	v_mov_b64_e32 v[78:79], v[164:165]
	v_mov_b64_e32 v[80:81], v[166:167]
	v_lshlrev_b32_e32 v84, 16, v78
	v_and_b32_e32 v85, 0xffff0000, v78
	v_lshlrev_b32_e32 v78, 16, v79
	v_and_b32_e32 v79, 0xffff0000, v79
	v_pk_add_f32 v[76:77], v[76:77], v[78:79]
	v_lshlrev_b32_e32 v78, 16, v80
	v_and_b32_e32 v79, 0xffff0000, v80
	v_lshlrev_b32_e32 v80, 16, v81
	v_and_b32_e32 v81, 0xffff0000, v81
	v_pk_add_f32 v[72:73], v[72:73], v[80:81]
	v_pk_add_f32 v[70:71], v[70:71], v[78:79]
	v_mov_b64_e32 v[78:79], v[168:169]
	v_mov_b64_e32 v[80:81], v[170:171]
	v_pk_add_f32 v[74:75], v[74:75], v[84:85]
	v_lshlrev_b32_e32 v84, 16, v78
	v_and_b32_e32 v85, 0xffff0000, v78
	v_lshlrev_b32_e32 v78, 16, v79
	v_and_b32_e32 v79, 0xffff0000, v79
	v_pk_add_f32 v[68:69], v[68:69], v[78:79]
	v_lshlrev_b32_e32 v78, 16, v80
	v_and_b32_e32 v79, 0xffff0000, v80
	v_lshlrev_b32_e32 v80, 16, v81
	v_and_b32_e32 v81, 0xffff0000, v81
	v_pk_add_f32 v[64:65], v[64:65], v[80:81]
	v_pk_add_f32 v[62:63], v[62:63], v[78:79]
	v_mov_b64_e32 v[78:79], v[172:173]
	v_mov_b64_e32 v[80:81], v[174:175]
	v_pk_add_f32 v[66:67], v[66:67], v[84:85]
	v_lshlrev_b32_e32 v84, 16, v78
	v_and_b32_e32 v85, 0xffff0000, v78
	v_lshlrev_b32_e32 v78, 16, v79
	v_and_b32_e32 v79, 0xffff0000, v79
	v_pk_add_f32 v[58:59], v[58:59], v[78:79]
	v_lshlrev_b32_e32 v78, 16, v80
	v_and_b32_e32 v79, 0xffff0000, v80
	v_lshlrev_b32_e32 v80, 16, v81
	v_and_b32_e32 v81, 0xffff0000, v81
	v_pk_add_f32 v[56:57], v[56:57], v[80:81]
	v_pk_add_f32 v[54:55], v[54:55], v[78:79]
	v_mov_b64_e32 v[78:79], v[176:177]
	v_mov_b64_e32 v[80:81], v[178:179]
	v_pk_add_f32 v[60:61], v[60:61], v[84:85]
	v_lshlrev_b32_e32 v82, 16, v78
	v_and_b32_e32 v83, 0xffff0000, v78
	v_lshlrev_b32_e32 v78, 16, v79
	v_and_b32_e32 v79, 0xffff0000, v79
	v_pk_add_f32 v[52:53], v[52:53], v[78:79]
	v_lshlrev_b32_e32 v78, 16, v80
	v_and_b32_e32 v79, 0xffff0000, v80
	v_lshlrev_b32_e32 v80, 16, v81
	v_and_b32_e32 v81, 0xffff0000, v81
	v_pk_add_f32 v[50:51], v[50:51], v[82:83]
	v_pk_add_f32 v[46:47], v[46:47], v[80:81]
	v_pk_add_f32 v[48:49], v[48:49], v[78:79]
.LBB0_623:
	v_mov_b32_e32 v80, v71
	v_mov_b32_e32 v81, v75
	v_mov_b32_e32 v78, v70
	v_mov_b32_e32 v79, v74
	v_pk_mul_f32 v[80:81], v[80:81], v[80:81]
	v_mov_b32_e32 v82, v73
	v_mov_b32_e32 v83, v77
	v_pk_fma_f32 v[78:79], v[78:79], v[78:79], v[80:81]
	v_mov_b32_e32 v80, v72
	v_mov_b32_e32 v81, v76
	v_pk_mul_f32 v[82:83], v[82:83], v[82:83]
	v_mul_f32_e32 v2, v62, v62
	v_pk_fma_f32 v[80:81], v[80:81], v[80:81], v[82:83]
	v_pk_mul_f32 v[82:83], v[66:67], v[66:67]
	v_pk_add_f32 v[78:79], v[78:79], v[80:81]
	v_pk_mul_f32 v[80:81], v[68:69], v[68:69]
	v_pk_add_f32 v[78:79], v[78:79], v[78:79] op_sel_hi:[0,1]
	v_pk_mov_b32 v[84:85], v[82:83], v[80:81] op_sel:[1,0]
	v_mov_b32_e32 v83, v81
	v_pk_add_f32 v[80:81], v[84:85], v[82:83]
	v_pk_fma_f32 v[82:83], v[62:63], v[62:63], v[2:3] op_sel_hi:[1,1,0]
	v_mul_f32_e32 v2, v64, v64
	v_pk_add_f32 v[80:81], v[80:81], v[80:81] op_sel_hi:[0,1]
	v_pk_fma_f32 v[84:85], v[64:65], v[64:65], v[2:3] op_sel_hi:[1,1,0]
	v_mul_f32_e32 v82, v60, v60
	v_mul_f32_e32 v84, v61, v61
	v_mul_f32_e32 v80, v58, v58
	v_mul_f32_e32 v78, v59, v59
	v_pk_add_f32 v[82:83], v[82:83], v[84:85]
	v_pk_add_f32 v[78:79], v[80:81], v[78:79]
	v_pk_mul_f32 v[80:81], v[56:57], v[56:57]
	v_pk_add_f32 v[78:79], v[82:83], v[78:79]
	v_pk_mul_f32 v[82:83], v[54:55], v[54:55]
	v_mul_f32_e32 v2, v50, v50
	v_pk_mov_b32 v[84:85], v[82:83], v[80:81] op_sel:[1,0]
	v_mov_b32_e32 v83, v81
	v_pk_add_f32 v[80:81], v[84:85], v[82:83]
	v_pk_fma_f32 v[82:83], v[50:51], v[50:51], v[2:3] op_sel_hi:[1,1,0]
	v_mul_f32_e32 v2, v52, v52
	v_pk_add_f32 v[78:79], v[78:79], v[78:79] op_sel_hi:[0,1]
	v_pk_add_f32 v[80:81], v[80:81], v[80:81] op_sel_hi:[0,1]
	v_pk_fma_f32 v[84:85], v[52:53], v[52:53], v[2:3] op_sel_hi:[1,1,0]
	v_mul_f32_e32 v82, v48, v48
	v_mul_f32_e32 v84, v49, v49
	v_mul_f32_e32 v80, v46, v46
	v_mul_f32_e32 v78, v47, v47
	v_pk_add_f32 v[82:83], v[82:83], v[84:85]
	v_pk_add_f32 v[78:79], v[80:81], v[78:79]
	v_mov_b32_e32 v37, v3
	v_pk_add_f32 v[78:79], v[82:83], v[78:79]
	s_lshl_b64 s[72:73], s[36:37], 11
	v_add_f32_e32 v2, v78, v79
	s_cmpk_lt_i32 s36, 0x2800
	s_cselect_b32 s16, 0x800, s41
	v_add_f32_dpp v2, v2, v2 quad_perm:[1,0,3,2] row_mask:0xf bank_mask:0xf bound_ctrl:1
	s_and_b64 s[12:13], s[68:69], exec
	s_cselect_b32 s12, 0, s16
	v_add_f32_dpp v2, v2, v2 quad_perm:[2,3,0,1] row_mask:0xf bank_mask:0xf bound_ctrl:1
	s_lshl_b32 s12, s12, 2
	s_lshl_b64 s[68:69], s[72:73], 1
	v_add_f32_dpp v2, v2, v2 row_ror:4 row_mask:0xf bank_mask:0xf bound_ctrl:1
	s_add_i32 s72, s36, 1
	s_cmpk_lt_i32 s72, 0x2000
	v_add_f32_dpp v2, v2, v2 row_ror:8 row_mask:0xf bank_mask:0xf bound_ctrl:1
	s_nop 1
	v_mov_b32_dpp v37, v2 row_bcast:15 row_mask:0xa bank_mask:0xf
	v_add_f32_e32 v2, v2, v37
	v_mov_b32_e32 v37, v3
	s_nop 1
	v_mov_b32_dpp v37, v2 row_bcast:31 row_mask:0xc bank_mask:0xf
	v_add_f32_e32 v2, v2, v37
	v_add_u32_e32 v37, s12, v1
	v_readlane_b32 s13, v2, 63
	ds_read_b128 v[78:81], v37
	ds_read_b128 v[82:85], v37 offset:16
	v_fma_f32 v2, s13, v245, v233
	v_rsq_f32_e32 v2, v2
	s_nop 0
	v_pk_mul_f32 v[74:75], v[2:3], v[74:75] op_sel_hi:[0,1]
	s_waitcnt lgkmcnt(1)
	v_pk_fma_f32 v[74:75], v[78:79], v[74:75], v[32:33]
	v_pk_mul_f32 v[32:33], v[2:3], v[72:73] op_sel_hi:[0,1]
	v_pk_mul_f32 v[76:77], v[2:3], v[76:77] op_sel_hi:[0,1]
	v_pk_mul_f32 v[70:71], v[2:3], v[70:71] op_sel_hi:[0,1]
	s_waitcnt lgkmcnt(0)
	v_pk_fma_f32 v[72:73], v[84:85], v[32:33], v[30:31]
	ds_read_b128 v[30:33], v37 offset:2048
	v_pk_fma_f32 v[34:35], v[80:81], v[76:77], v[34:35]
	v_pk_fma_f32 v[70:71], v[82:83], v[70:71], v[28:29]
	v_pk_mul_f32 v[28:29], v[2:3], v[66:67] op_sel_hi:[0,1]
	v_pk_mul_f32 v[76:77], v[2:3], v[68:69] op_sel_hi:[0,1]
	ds_read_b128 v[66:69], v37 offset:2064
	s_waitcnt lgkmcnt(1)
	v_pk_fma_f32 v[30:31], v[30:31], v[28:29], v[24:25]
	v_pk_mul_f32 v[24:25], v[2:3], v[64:65] op_sel_hi:[0,1]
	v_pk_fma_f32 v[32:33], v[32:33], v[76:77], v[26:27]
	v_pk_mul_f32 v[26:27], v[2:3], v[62:63] op_sel_hi:[0,1]
	s_waitcnt lgkmcnt(0)
	v_pk_fma_f32 v[62:63], v[68:69], v[24:25], v[22:23]
	ds_read_b128 v[22:25], v37 offset:4096
	v_pk_fma_f32 v[64:65], v[66:67], v[26:27], v[20:21]
	ds_read_b128 v[26:29], v37 offset:4112
	v_pk_mul_f32 v[20:21], v[2:3], v[60:61] op_sel_hi:[0,1]
	v_pk_mul_f32 v[58:59], v[2:3], v[58:59] op_sel_hi:[0,1]
	s_waitcnt lgkmcnt(1)
	v_pk_fma_f32 v[22:23], v[22:23], v[20:21], v[16:17]
	v_pk_mul_f32 v[16:17], v[2:3], v[56:57] op_sel_hi:[0,1]
	v_pk_fma_f32 v[24:25], v[24:25], v[58:59], v[18:19]
	v_pk_mul_f32 v[18:19], v[2:3], v[54:55] op_sel_hi:[0,1]
	s_waitcnt lgkmcnt(0)
	v_pk_fma_f32 v[28:29], v[28:29], v[16:17], v[14:15]
	ds_read_b128 v[14:17], v37 offset:6144
	v_pk_fma_f32 v[26:27], v[26:27], v[18:19], v[12:13]
	ds_read_b128 v[18:21], v37 offset:6160
	v_pk_mul_f32 v[12:13], v[2:3], v[50:51] op_sel_hi:[0,1]
	v_pk_mul_f32 v[50:51], v[2:3], v[52:53] op_sel_hi:[0,1]
	s_waitcnt lgkmcnt(1)
	v_pk_fma_f32 v[50:51], v[50:51], v[16:17], v[10:11]
	v_pk_fma_f32 v[52:53], v[12:13], v[14:15], v[8:9]
	v_pk_mul_f32 v[8:9], v[2:3], v[48:49] op_sel_hi:[0,1]
	v_pk_mul_f32 v[10:11], v[2:3], v[46:47] op_sel_hi:[0,1]
	s_waitcnt lgkmcnt(0)
	v_pk_fma_f32 v[20:21], v[10:11], v[20:21], v[6:7]
	v_pk_fma_f32 v[46:47], v[8:9], v[18:19], v[4:5]
	v_lshl_add_u64 v[8:9], v[40:41], 0, s[68:69]
	v_cvt_pk_bf16_f32 v4, v74, v75
	v_cvt_pk_bf16_f32 v5, v34, v35
	v_cvt_pk_bf16_f32 v6, v70, v71
	v_cvt_pk_bf16_f32 v7, v72, v73
	global_store_dwordx4 v[8:9], v[4:7], off
	v_mul_f32_e32 v2, v64, v64
	s_nop 0
	v_cvt_pk_bf16_f32 v4, v30, v31
	v_cvt_pk_bf16_f32 v5, v32, v33
	v_cvt_pk_bf16_f32 v6, v64, v65
	v_cvt_pk_bf16_f32 v7, v62, v63
	global_store_dwordx4 v[8:9], v[4:7], off offset:1024
	s_nop 1
	v_cvt_pk_bf16_f32 v4, v22, v23
	v_cvt_pk_bf16_f32 v5, v24, v25
	v_cvt_pk_bf16_f32 v6, v26, v27
	v_cvt_pk_bf16_f32 v7, v28, v29
	global_store_dwordx4 v[8:9], v[4:7], off offset:2048
	s_nop 1
	v_cvt_pk_bf16_f32 v4, v52, v53
	v_cvt_pk_bf16_f32 v5, v50, v51
	v_cvt_pk_bf16_f32 v6, v46, v47
	v_cvt_pk_bf16_f32 v7, v20, v21
	global_store_dwordx4 v[8:9], v[4:7], off offset:3072
	v_mov_b32_e32 v8, v35
	v_mov_b32_e32 v9, v73
	v_mov_b32_e32 v6, v75
	v_mov_b32_e32 v7, v71
	v_mov_b32_e32 v4, v74
	v_mov_b32_e32 v5, v70
	v_pk_mul_f32 v[6:7], v[6:7], v[6:7]
	v_pk_mul_f32 v[8:9], v[8:9], v[8:9]
	v_pk_fma_f32 v[4:5], v[4:5], v[4:5], v[6:7]
	v_mov_b32_e32 v6, v34
	v_mov_b32_e32 v7, v72
	v_pk_fma_f32 v[6:7], v[6:7], v[6:7], v[8:9]
	v_pk_mul_f32 v[8:9], v[30:31], v[30:31]
	v_pk_add_f32 v[4:5], v[4:5], v[6:7]
	v_pk_mul_f32 v[6:7], v[32:33], v[32:33]
	v_pk_add_f32 v[4:5], v[4:5], v[4:5] op_sel_hi:[0,1]
	v_pk_mov_b32 v[10:11], v[8:9], v[6:7] op_sel:[1,0]
	v_mov_b32_e32 v9, v7
	v_pk_add_f32 v[6:7], v[10:11], v[8:9]
	v_pk_fma_f32 v[8:9], v[64:65], v[64:65], v[2:3] op_sel_hi:[1,1,0]
	v_mul_f32_e32 v2, v62, v62
	v_pk_add_f32 v[6:7], v[6:7], v[6:7] op_sel_hi:[0,1]
	v_pk_fma_f32 v[10:11], v[62:63], v[62:63], v[2:3] op_sel_hi:[1,1,0]
	v_mul_f32_e32 v8, v22, v22
	v_mul_f32_e32 v10, v23, v23
	v_mul_f32_e32 v6, v24, v24
	v_mul_f32_e32 v4, v25, v25
	v_pk_add_f32 v[8:9], v[8:9], v[10:11]
	v_pk_add_f32 v[4:5], v[6:7], v[4:5]
	v_pk_mul_f32 v[6:7], v[28:29], v[28:29]
	v_pk_add_f32 v[4:5], v[8:9], v[4:5]
	v_pk_mul_f32 v[8:9], v[26:27], v[26:27]
	v_mul_f32_e32 v2, v52, v52
	v_pk_mov_b32 v[10:11], v[8:9], v[6:7] op_sel:[1,0]
	v_mov_b32_e32 v9, v7
	v_pk_add_f32 v[6:7], v[10:11], v[8:9]
	v_pk_fma_f32 v[8:9], v[52:53], v[52:53], v[2:3] op_sel_hi:[1,1,0]
	v_mul_f32_e32 v2, v50, v50
	v_pk_add_f32 v[4:5], v[4:5], v[4:5] op_sel_hi:[0,1]
	v_pk_add_f32 v[6:7], v[6:7], v[6:7] op_sel_hi:[0,1]
	v_pk_fma_f32 v[10:11], v[50:51], v[50:51], v[2:3] op_sel_hi:[1,1,0]
	v_mul_f32_e32 v8, v46, v46
	v_mul_f32_e32 v10, v47, v47
	v_mul_f32_e32 v6, v20, v20
	v_mul_f32_e32 v4, v21, v21
	v_pk_add_f32 v[8:9], v[8:9], v[10:11]
	v_pk_add_f32 v[4:5], v[6:7], v[4:5]
	s_nop 0
	v_pk_add_f32 v[4:5], v[8:9], v[4:5]
	s_nop 0
	v_add_f32_e32 v2, v4, v5
	v_mov_b32_e32 v4, v3
	s_nop 0
	v_add_f32_dpp v2, v2, v2 quad_perm:[1,0,3,2] row_mask:0xf bank_mask:0xf bound_ctrl:1
	s_nop 1
	v_add_f32_dpp v2, v2, v2 quad_perm:[2,3,0,1] row_mask:0xf bank_mask:0xf bound_ctrl:1
	s_nop 1
	v_add_f32_dpp v2, v2, v2 row_ror:4 row_mask:0xf bank_mask:0xf bound_ctrl:1
	s_nop 1
	v_add_f32_dpp v2, v2, v2 row_ror:8 row_mask:0xf bank_mask:0xf bound_ctrl:1
	s_nop 1
	v_mov_b32_dpp v4, v2 row_bcast:15 row_mask:0xa bank_mask:0xf
	v_add_f32_e32 v2, v2, v4
	v_mov_b32_e32 v4, v3
	s_nop 1
	v_mov_b32_dpp v4, v2 row_bcast:31 row_mask:0xc bank_mask:0xf
	v_add_f32_e32 v2, v2, v4
	ds_read_b128 v[4:7], v37 offset:49152
	ds_read_b128 v[8:11], v37 offset:24576
	ds_read_b128 v[12:15], v37 offset:24592
	ds_read_b128 v[16:19], v37 offset:49168
	v_readlane_b32 s12, v2, 63
	s_nop 1
	v_fma_f32 v2, s12, v245, v233
	v_rsq_f32_e32 v2, v2
	s_nop 0
	v_pk_mul_f32 v[48:49], v[74:75], v[2:3] op_sel_hi:[1,0]
	v_pk_mul_f32 v[34:35], v[34:35], v[2:3] op_sel_hi:[1,0]
	s_waitcnt lgkmcnt(2)
	v_pk_fma_f32 v[4:5], v[8:9], v[48:49], v[4:5]
	v_pk_fma_f32 v[6:7], v[10:11], v[34:35], v[6:7]
	v_pk_mul_f32 v[8:9], v[70:71], v[2:3] op_sel_hi:[1,0]
	v_pk_mul_f32 v[10:11], v[72:73], v[2:3] op_sel_hi:[1,0]
	s_waitcnt lgkmcnt(0)
	v_pk_fma_f32 v[8:9], v[12:13], v[8:9], v[16:17]
	v_pk_fma_f32 v[10:11], v[14:15], v[10:11], v[18:19]
	v_cvt_pk_bf16_f32 v4, v4, v5
	v_cvt_pk_bf16_f32 v5, v6, v7
	v_cvt_pk_bf16_f32 v6, v8, v9
	v_cvt_pk_bf16_f32 v7, v10, v11
	v_lshl_add_u64 v[34:35], v[44:45], 0, s[68:69]
	global_store_dwordx4 v[34:35], v[4:7], off
	ds_read_b128 v[4:7], v37 offset:51200
	ds_read_b128 v[8:11], v37 offset:26624
	ds_read_b128 v[12:15], v37 offset:26640
	ds_read_b128 v[16:19], v37 offset:51216
	v_pk_mul_f32 v[30:31], v[30:31], v[2:3] op_sel_hi:[1,0]
	v_pk_mul_f32 v[32:33], v[32:33], v[2:3] op_sel_hi:[1,0]
	s_waitcnt lgkmcnt(2)
	v_pk_fma_f32 v[4:5], v[30:31], v[8:9], v[4:5]
	v_pk_fma_f32 v[6:7], v[32:33], v[10:11], v[6:7]
	v_pk_mul_f32 v[8:9], v[64:65], v[2:3] op_sel_hi:[1,0]
	v_pk_mul_f32 v[10:11], v[62:63], v[2:3] op_sel_hi:[1,0]
	s_waitcnt lgkmcnt(0)
	v_pk_fma_f32 v[8:9], v[8:9], v[12:13], v[16:17]
	v_pk_fma_f32 v[10:11], v[10:11], v[14:15], v[18:19]
	v_cvt_pk_bf16_f32 v4, v4, v5
	v_cvt_pk_bf16_f32 v5, v6, v7
	v_cvt_pk_bf16_f32 v6, v8, v9
	v_cvt_pk_bf16_f32 v7, v10, v11
	global_store_dwordx4 v[34:35], v[4:7], off offset:1024
	ds_read_b128 v[4:7], v37 offset:53248
	ds_read_b128 v[8:11], v37 offset:28672
	ds_read_b128 v[12:15], v37 offset:28688
	ds_read_b128 v[16:19], v37 offset:53264
	v_pk_mul_f32 v[22:23], v[22:23], v[2:3] op_sel_hi:[1,0]
	v_pk_mul_f32 v[24:25], v[24:25], v[2:3] op_sel_hi:[1,0]
	s_waitcnt lgkmcnt(2)
	v_pk_fma_f32 v[4:5], v[22:23], v[8:9], v[4:5]
	v_pk_fma_f32 v[6:7], v[24:25], v[10:11], v[6:7]
	v_pk_mul_f32 v[8:9], v[26:27], v[2:3] op_sel_hi:[1,0]
	v_pk_mul_f32 v[10:11], v[28:29], v[2:3] op_sel_hi:[1,0]
	s_waitcnt lgkmcnt(0)
	v_pk_fma_f32 v[8:9], v[8:9], v[12:13], v[16:17]
	v_pk_fma_f32 v[10:11], v[10:11], v[14:15], v[18:19]
	v_cvt_pk_bf16_f32 v4, v4, v5
	v_cvt_pk_bf16_f32 v5, v6, v7
	v_cvt_pk_bf16_f32 v6, v8, v9
	v_cvt_pk_bf16_f32 v7, v10, v11
	global_store_dwordx4 v[34:35], v[4:7], off offset:2048
	ds_read_b128 v[4:7], v37 offset:55296
	ds_read_b128 v[8:11], v37 offset:30720
	ds_read_b128 v[12:15], v37 offset:30736
	ds_read_b128 v[16:19], v37 offset:55312
	v_pk_mul_f32 v[22:23], v[52:53], v[2:3] op_sel_hi:[1,0]
	v_pk_mul_f32 v[24:25], v[50:51], v[2:3] op_sel_hi:[1,0]
	s_waitcnt lgkmcnt(2)
	v_pk_fma_f32 v[4:5], v[22:23], v[8:9], v[4:5]
	v_pk_fma_f32 v[6:7], v[24:25], v[10:11], v[6:7]
	v_pk_mul_f32 v[8:9], v[46:47], v[2:3] op_sel_hi:[1,0]
	v_pk_mul_f32 v[10:11], v[20:21], v[2:3] op_sel_hi:[1,0]
	s_waitcnt lgkmcnt(0)
	v_pk_fma_f32 v[8:9], v[8:9], v[12:13], v[16:17]
	v_pk_fma_f32 v[10:11], v[10:11], v[14:15], v[18:19]
	s_cselect_b64 s[68:69], -1, 0
	s_cmpk_gt_i32 s72, 0x1fff
	v_cvt_pk_bf16_f32 v4, v4, v5
	v_cvt_pk_bf16_f32 v5, v6, v7
	v_cvt_pk_bf16_f32 v6, v8, v9
	v_cvt_pk_bf16_f32 v7, v10, v11
	s_cselect_b64 s[74:75], -1, 0
	s_andn2_b64 vcc, exec, s[0:1]
	global_store_dwordx4 v[34:35], v[4:7], off offset:3072
	s_cbranch_vccnz .LBB0_625
	s_ashr_i32 s73, s72, 31
	s_lshl_b64 s[12:13], s[72:73], 12
	v_lshl_add_u64 v[16:17], v[40:41], 0, s[12:13]
	v_mov_b64_e32 v[4:5], v[116:117]
	v_mov_b64_e32 v[6:7], v[118:119]
	v_mov_b64_e32 v[8:9], v[120:121]
	v_mov_b64_e32 v[10:11], v[122:123]
	v_mov_b64_e32 v[12:13], v[124:125]
	v_mov_b64_e32 v[14:15], v[126:127]
	v_mov_b64_e32 v[46:47], v[128:129]
	v_mov_b64_e32 v[48:49], v[130:131]
	v_lshlrev_b32_e32 v32, 16, v4
	v_and_b32_e32 v33, 0xffff0000, v4
	v_lshlrev_b32_e32 v34, 16, v5
	v_and_b32_e32 v35, 0xffff0000, v5
	v_lshlrev_b32_e32 v28, 16, v6
	v_and_b32_e32 v29, 0xffff0000, v6
	v_lshlrev_b32_e32 v30, 16, v7
	v_and_b32_e32 v31, 0xffff0000, v7
	v_lshlrev_b32_e32 v24, 16, v8
	v_and_b32_e32 v25, 0xffff0000, v8
	v_lshlrev_b32_e32 v26, 16, v9
	v_and_b32_e32 v27, 0xffff0000, v9
	v_lshlrev_b32_e32 v20, 16, v10
	v_and_b32_e32 v21, 0xffff0000, v10
	v_lshlrev_b32_e32 v22, 16, v11
	v_and_b32_e32 v23, 0xffff0000, v11
	v_lshlrev_b32_e32 v16, 16, v12
	v_and_b32_e32 v17, 0xffff0000, v12
	v_lshlrev_b32_e32 v18, 16, v13
	v_and_b32_e32 v19, 0xffff0000, v13
	v_lshlrev_b32_e32 v12, 16, v14
	v_and_b32_e32 v13, 0xffff0000, v14
	v_lshlrev_b32_e32 v14, 16, v15
	v_and_b32_e32 v15, 0xffff0000, v15
	v_lshlrev_b32_e32 v8, 16, v46
	v_and_b32_e32 v9, 0xffff0000, v46
	v_lshlrev_b32_e32 v10, 16, v47
	v_and_b32_e32 v11, 0xffff0000, v47
	v_lshlrev_b32_e32 v4, 16, v48
	v_and_b32_e32 v5, 0xffff0000, v48
	v_lshlrev_b32_e32 v6, 16, v49
	v_and_b32_e32 v7, 0xffff0000, v49
	s_cbranch_execz .LBB0_626
	s_branch .LBB0_631

.LBB0_631:
	s_lshl_b64 s[12:13], s[72:73], 12
	v_lshl_add_u64 v[58:59], v[38:39], 0, s[12:13]
	v_mov_b64_e32 v[46:47], v[148:149]
	v_mov_b64_e32 v[48:49], v[150:151]
	v_mov_b64_e32 v[50:51], v[152:153]
	v_mov_b64_e32 v[52:53], v[154:155]
	v_mov_b64_e32 v[54:55], v[156:157]
	v_mov_b64_e32 v[56:57], v[158:159]
	v_mov_b64_e32 v[78:79], v[160:161]
	v_mov_b64_e32 v[80:81], v[162:163]
	s_cmpk_lt_i32 s36, 0x1fff
	s_waitcnt vmcnt(0)
	v_lshlrev_b32_e32 v74, 16, v46
	v_and_b32_e32 v75, 0xffff0000, v46
	v_lshlrev_b32_e32 v76, 16, v47
	v_and_b32_e32 v77, 0xffff0000, v47
	v_lshlrev_b32_e32 v70, 16, v48
	v_and_b32_e32 v71, 0xffff0000, v48
	v_lshlrev_b32_e32 v72, 16, v49
	v_and_b32_e32 v73, 0xffff0000, v49
	v_lshlrev_b32_e32 v66, 16, v50
	v_and_b32_e32 v67, 0xffff0000, v50
	v_lshlrev_b32_e32 v68, 16, v51
	v_and_b32_e32 v69, 0xffff0000, v51
	v_lshlrev_b32_e32 v62, 16, v52
	v_and_b32_e32 v63, 0xffff0000, v52
	v_lshlrev_b32_e32 v64, 16, v53
	v_and_b32_e32 v65, 0xffff0000, v53
	v_lshlrev_b32_e32 v60, 16, v54
	v_and_b32_e32 v61, 0xffff0000, v54
	v_lshlrev_b32_e32 v58, 16, v55
	v_and_b32_e32 v59, 0xffff0000, v55
	v_lshlrev_b32_e32 v54, 16, v56
	v_and_b32_e32 v55, 0xffff0000, v56
	v_lshlrev_b32_e32 v56, 16, v57
	v_and_b32_e32 v57, 0xffff0000, v57
	v_lshlrev_b32_e32 v50, 16, v78
	v_and_b32_e32 v51, 0xffff0000, v78
	v_lshlrev_b32_e32 v52, 16, v79
	v_and_b32_e32 v53, 0xffff0000, v79
	v_lshlrev_b32_e32 v48, 16, v80
	v_and_b32_e32 v49, 0xffff0000, v80
	v_lshlrev_b32_e32 v46, 16, v81
	v_and_b32_e32 v47, 0xffff0000, v81
	s_cbranch_scc1 .LBB0_612
	s_add_i32 s64, s36, 0xffffe001
	s_lshl_b64 s[12:13], s[64:65], 12
	v_lshl_add_u64 v[82:83], v[42:43], 0, s[12:13]
	v_mov_b64_e32 v[78:79], v[180:181]
	v_mov_b64_e32 v[80:81], v[182:183]
	v_lshlrev_b32_e32 v84, 16, v78
	v_and_b32_e32 v85, 0xffff0000, v78
	v_lshlrev_b32_e32 v78, 16, v79
	v_and_b32_e32 v79, 0xffff0000, v79
	v_pk_add_f32 v[76:77], v[76:77], v[78:79]
	v_lshlrev_b32_e32 v78, 16, v80
	v_and_b32_e32 v79, 0xffff0000, v80
	v_lshlrev_b32_e32 v80, 16, v81
	v_and_b32_e32 v81, 0xffff0000, v81
	v_pk_add_f32 v[72:73], v[72:73], v[80:81]
	v_pk_add_f32 v[70:71], v[70:71], v[78:79]
	v_mov_b64_e32 v[78:79], v[184:185]
	v_mov_b64_e32 v[80:81], v[186:187]
	v_pk_add_f32 v[74:75], v[74:75], v[84:85]
	v_lshlrev_b32_e32 v84, 16, v78
	v_and_b32_e32 v85, 0xffff0000, v78
	v_lshlrev_b32_e32 v78, 16, v79
	v_and_b32_e32 v79, 0xffff0000, v79
	v_pk_add_f32 v[68:69], v[68:69], v[78:79]
	v_lshlrev_b32_e32 v78, 16, v80
	v_and_b32_e32 v79, 0xffff0000, v80
	v_lshlrev_b32_e32 v80, 16, v81
	v_and_b32_e32 v81, 0xffff0000, v81
	v_pk_add_f32 v[64:65], v[64:65], v[80:81]
	v_pk_add_f32 v[62:63], v[62:63], v[78:79]
	v_mov_b64_e32 v[78:79], v[188:189]
	v_mov_b64_e32 v[80:81], v[190:191]
	v_pk_add_f32 v[66:67], v[66:67], v[84:85]
	v_lshlrev_b32_e32 v84, 16, v78
	v_and_b32_e32 v85, 0xffff0000, v78
	v_lshlrev_b32_e32 v78, 16, v79
	v_and_b32_e32 v79, 0xffff0000, v79
	v_pk_add_f32 v[58:59], v[58:59], v[78:79]
	v_lshlrev_b32_e32 v78, 16, v80
	v_and_b32_e32 v79, 0xffff0000, v80
	v_lshlrev_b32_e32 v80, 16, v81
	v_and_b32_e32 v81, 0xffff0000, v81
	v_pk_add_f32 v[56:57], v[56:57], v[80:81]
	v_pk_add_f32 v[54:55], v[54:55], v[78:79]
	v_mov_b64_e32 v[78:79], v[192:193]
	v_mov_b64_e32 v[80:81], v[194:195]
	v_pk_add_f32 v[60:61], v[60:61], v[84:85]
	v_lshlrev_b32_e32 v82, 16, v78
	v_and_b32_e32 v83, 0xffff0000, v78
	v_lshlrev_b32_e32 v78, 16, v79
	v_and_b32_e32 v79, 0xffff0000, v79
	v_pk_add_f32 v[52:53], v[52:53], v[78:79]
	v_lshlrev_b32_e32 v78, 16, v80
	v_and_b32_e32 v79, 0xffff0000, v80
	v_lshlrev_b32_e32 v80, 16, v81
	v_and_b32_e32 v81, 0xffff0000, v81
	v_pk_add_f32 v[50:51], v[50:51], v[82:83]
	v_pk_add_f32 v[46:47], v[46:47], v[80:81]
	v_pk_add_f32 v[48:49], v[48:49], v[78:79]
	s_branch .LBB0_612
